# pre-pass: GLA low-rank gate rows staged once per wave through an LDS tile (broadcast ds_reads, pipelined), HGRN q loads issued with the f loads
# speedup vs baseline: 1.0190x; 1.0058x over previous
.Lpre_init:
	v_and_b32_e32 v140, 0x7f, v156
	v_lshlrev_b32_e32 v141, 1, v140
	v_lshlrev_b32_e32 v140, 2, v140
	v_and_b32_e32 v142, 63, v156
	v_lshlrev_b32_e32 v143, 1, v142
	v_lshlrev_b32_e32 v142, 2, v142
	v_lshlrev_b32_e32 v144, 2, v156
	v_lshrrev_b32_e32 v32, 6, v156
	s_nop 1
	v_readfirstlane_b32 s17, v32
	v_and_b32_e32 v146, 63, v156
	v_lshlrev_b32_e32 v146, 4, v146
	s_lshl_b32 s4, s17, 10
	s_add_u32 s4, s4, 0x400
	v_mov_b32_e32 v81, s4
	v_add_u32_e32 v147, s4, v146
	s_mov_b32 s10, 0x3fb8aa3b
	s_mov_b32 s11, 0xbfb8aa3b
	s_mov_b32 s12, 0x3f317218
	s_mov_b32 s13, 0x3d800000
	s_bfe_u32 s18, s88, 0x20001
	s_bitcmp1_b32 s88, 0
	s_cbranch_scc1 .Lpre_g_init

.Lpre_h_go:
	s_lshl_b32 s21, s20, 11
	s_lshl_b32 s4, s18, 9
	s_add_u32 s21, s21, s4
	s_add_u32 s22, s21, 0xc180000
	s_add_u32 s24, s94, s22
	s_addc_u32 s25, s95, 0
	s_lshl_b32 s21, s20, 10
	s_lshl_b32 s4, s18, 8
	s_add_u32 s21, s21, s4
	s_add_u32 s22, s21, 0x8100000
	s_add_u32 s26, s94, s22
	s_addc_u32 s27, s95, 0
	s_mov_b64 s[28:29], s[26:27]
	s_add_u32 s22, s21, 0x2a540000
	s_add_u32 s30, s94, s22
	s_addc_u32 s31, s95, 0
	global_load_dword v64, v140, s[24:25]
	global_load_dword v65, v140, s[24:25] offset:2048
	s_add_u32 s24, s24, 0x1000
	s_addc_u32 s25, s25, 0
	global_load_dword v66, v140, s[24:25]
	global_load_dword v67, v140, s[24:25] offset:2048
	s_add_u32 s24, s24, 0x1000
	s_addc_u32 s25, s25, 0
	global_load_dword v68, v140, s[24:25]
	global_load_dword v69, v140, s[24:25] offset:2048
	s_add_u32 s24, s24, 0x1000
	s_addc_u32 s25, s25, 0
	global_load_dword v70, v140, s[24:25]
	global_load_dword v71, v140, s[24:25] offset:2048
	s_add_u32 s24, s24, 0x1000
	s_addc_u32 s25, s25, 0
	global_load_dword v72, v140, s[24:25]
	global_load_dword v73, v140, s[24:25] offset:2048
	s_add_u32 s24, s24, 0x1000
	s_addc_u32 s25, s25, 0
	global_load_dword v74, v140, s[24:25]
	global_load_dword v75, v140, s[24:25] offset:2048
	s_add_u32 s24, s24, 0x1000
	s_addc_u32 s25, s25, 0
	global_load_dword v76, v140, s[24:25]
	global_load_dword v77, v140, s[24:25] offset:2048
	s_add_u32 s24, s24, 0x1000
	s_addc_u32 s25, s25, 0
	global_load_dword v78, v140, s[24:25]
	global_load_dword v79, v140, s[24:25] offset:2048
	s_add_u32 s24, s24, 0x1000
	s_addc_u32 s25, s25, 0
	global_load_dword v80, v140, s[24:25]
	global_load_dword v81, v140, s[24:25] offset:2048
	s_add_u32 s24, s24, 0x1000
	s_addc_u32 s25, s25, 0
	global_load_dword v82, v140, s[24:25]
	global_load_dword v83, v140, s[24:25] offset:2048
	s_add_u32 s24, s24, 0x1000
	s_addc_u32 s25, s25, 0
	global_load_dword v84, v140, s[24:25]
	global_load_dword v85, v140, s[24:25] offset:2048
	s_add_u32 s24, s24, 0x1000
	s_addc_u32 s25, s25, 0
	global_load_dword v86, v140, s[24:25]
	global_load_dword v87, v140, s[24:25] offset:2048
	s_add_u32 s24, s24, 0x1000
	s_addc_u32 s25, s25, 0
	global_load_dword v88, v140, s[24:25]
	global_load_dword v89, v140, s[24:25] offset:2048
	s_add_u32 s24, s24, 0x1000
	s_addc_u32 s25, s25, 0
	global_load_dword v90, v140, s[24:25]
	global_load_dword v91, v140, s[24:25] offset:2048
	s_add_u32 s24, s24, 0x1000
	s_addc_u32 s25, s25, 0
	global_load_dword v92, v140, s[24:25]
	global_load_dword v93, v140, s[24:25] offset:2048
	s_add_u32 s24, s24, 0x1000
	s_addc_u32 s25, s25, 0
	global_load_dword v94, v140, s[24:25]
	global_load_dword v95, v140, s[24:25] offset:2048
	global_load_ushort v0, v141, s[26:27]
	global_load_ushort v1, v141, s[26:27] offset:1024
	global_load_ushort v2, v141, s[26:27] offset:2048
	global_load_ushort v3, v141, s[26:27] offset:3072
	s_add_u32 s26, s26, 0x1000
	s_addc_u32 s27, s27, 0
	global_load_ushort v4, v141, s[26:27]
	global_load_ushort v5, v141, s[26:27] offset:1024
	global_load_ushort v6, v141, s[26:27] offset:2048
	global_load_ushort v7, v141, s[26:27] offset:3072
	s_add_u32 s26, s26, 0x1000
	s_addc_u32 s27, s27, 0
	global_load_ushort v8, v141, s[26:27]
	global_load_ushort v9, v141, s[26:27] offset:1024
	global_load_ushort v10, v141, s[26:27] offset:2048
	global_load_ushort v11, v141, s[26:27] offset:3072
	s_add_u32 s26, s26, 0x1000
	s_addc_u32 s27, s27, 0
	global_load_ushort v12, v141, s[26:27]
	global_load_ushort v13, v141, s[26:27] offset:1024
	global_load_ushort v14, v141, s[26:27] offset:2048
	global_load_ushort v15, v141, s[26:27] offset:3072
	s_add_u32 s26, s26, 0x1000
	s_addc_u32 s27, s27, 0
	global_load_ushort v16, v141, s[26:27]
	global_load_ushort v17, v141, s[26:27] offset:1024
	global_load_ushort v18, v141, s[26:27] offset:2048
	global_load_ushort v19, v141, s[26:27] offset:3072
	s_add_u32 s26, s26, 0x1000
	s_addc_u32 s27, s27, 0
	global_load_ushort v20, v141, s[26:27]
	global_load_ushort v21, v141, s[26:27] offset:1024
	global_load_ushort v22, v141, s[26:27] offset:2048
	global_load_ushort v23, v141, s[26:27] offset:3072
	s_add_u32 s26, s26, 0x1000
	s_addc_u32 s27, s27, 0
	global_load_ushort v24, v141, s[26:27]
	global_load_ushort v25, v141, s[26:27] offset:1024
	global_load_ushort v26, v141, s[26:27] offset:2048
	global_load_ushort v27, v141, s[26:27] offset:3072
	s_add_u32 s26, s26, 0x1000
	s_addc_u32 s27, s27, 0
	global_load_ushort v28, v141, s[26:27]
	global_load_ushort v29, v141, s[26:27] offset:1024
	global_load_ushort v30, v141, s[26:27] offset:2048
	global_load_ushort v31, v141, s[26:27] offset:3072
	v_mov_b32_e32 v145, 0
	s_waitcnt vmcnt(60)
	v_log_f32_e32 v96, v64
	v_log_f32_e32 v97, v65
	v_log_f32_e32 v98, v66
	v_log_f32_e32 v99, v67
	v_sub_f32_e32 v64, 1.0, v64
	v_sub_f32_e32 v65, 1.0, v65
	v_sub_f32_e32 v66, 1.0, v66
	v_sub_f32_e32 v67, 1.0, v67
	v_mul_f32_e32 v96, s12, v96
	v_mul_f32_e32 v97, s12, v97
	v_mul_f32_e32 v98, s12, v98
	v_mul_f32_e32 v99, s12, v99
	v_add_f32_e32 v145, v145, v96
	v_add_f32_e32 v145, v145, v97
	v_add_f32_e32 v145, v145, v98
	v_add_f32_e32 v145, v145, v99
	s_waitcnt vmcnt(56)
	v_log_f32_e32 v100, v68
	v_log_f32_e32 v101, v69
	v_log_f32_e32 v102, v70
	v_log_f32_e32 v103, v71
	v_sub_f32_e32 v68, 1.0, v68
	v_sub_f32_e32 v69, 1.0, v69
	v_sub_f32_e32 v70, 1.0, v70
	v_sub_f32_e32 v71, 1.0, v71
	v_mul_f32_e32 v100, s12, v100
	v_mul_f32_e32 v101, s12, v101
	v_mul_f32_e32 v102, s12, v102
	v_mul_f32_e32 v103, s12, v103
	v_add_f32_e32 v145, v145, v100
	v_add_f32_e32 v145, v145, v101
	v_add_f32_e32 v145, v145, v102
	v_add_f32_e32 v145, v145, v103
	s_waitcnt vmcnt(52)
	v_log_f32_e32 v104, v72
	v_log_f32_e32 v105, v73
	v_log_f32_e32 v106, v74
	v_log_f32_e32 v107, v75
	v_sub_f32_e32 v72, 1.0, v72
	v_sub_f32_e32 v73, 1.0, v73
	v_sub_f32_e32 v74, 1.0, v74
	v_sub_f32_e32 v75, 1.0, v75
	v_mul_f32_e32 v104, s12, v104
	v_mul_f32_e32 v105, s12, v105
	v_mul_f32_e32 v106, s12, v106
	v_mul_f32_e32 v107, s12, v107
	v_add_f32_e32 v145, v145, v104
	v_add_f32_e32 v145, v145, v105
	v_add_f32_e32 v145, v145, v106
	v_add_f32_e32 v145, v145, v107
	s_waitcnt vmcnt(48)
	v_log_f32_e32 v108, v76
	v_log_f32_e32 v109, v77
	v_log_f32_e32 v110, v78
	v_log_f32_e32 v111, v79
	v_sub_f32_e32 v76, 1.0, v76
	v_sub_f32_e32 v77, 1.0, v77
	v_sub_f32_e32 v78, 1.0, v78
	v_sub_f32_e32 v79, 1.0, v79
	v_mul_f32_e32 v108, s12, v108
	v_mul_f32_e32 v109, s12, v109
	v_mul_f32_e32 v110, s12, v110
	v_mul_f32_e32 v111, s12, v111
	v_add_f32_e32 v145, v145, v108
	v_add_f32_e32 v145, v145, v109
	v_add_f32_e32 v145, v145, v110
	v_add_f32_e32 v145, v145, v111
	s_waitcnt vmcnt(44)
	v_log_f32_e32 v112, v80
	v_log_f32_e32 v113, v81
	v_log_f32_e32 v114, v82
	v_log_f32_e32 v115, v83
	v_sub_f32_e32 v80, 1.0, v80
	v_sub_f32_e32 v81, 1.0, v81
	v_sub_f32_e32 v82, 1.0, v82
	v_sub_f32_e32 v83, 1.0, v83
	v_mul_f32_e32 v112, s12, v112
	v_mul_f32_e32 v113, s12, v113
	v_mul_f32_e32 v114, s12, v114
	v_mul_f32_e32 v115, s12, v115
	v_add_f32_e32 v145, v145, v112
	v_add_f32_e32 v145, v145, v113
	v_add_f32_e32 v145, v145, v114
	v_add_f32_e32 v145, v145, v115
	s_waitcnt vmcnt(40)
	v_log_f32_e32 v116, v84
	v_log_f32_e32 v117, v85
	v_log_f32_e32 v118, v86
	v_log_f32_e32 v119, v87
	v_sub_f32_e32 v84, 1.0, v84
	v_sub_f32_e32 v85, 1.0, v85
	v_sub_f32_e32 v86, 1.0, v86
	v_sub_f32_e32 v87, 1.0, v87
	v_mul_f32_e32 v116, s12, v116
	v_mul_f32_e32 v117, s12, v117
	v_mul_f32_e32 v118, s12, v118
	v_mul_f32_e32 v119, s12, v119
	v_add_f32_e32 v145, v145, v116
	v_add_f32_e32 v145, v145, v117
	v_add_f32_e32 v145, v145, v118
	v_add_f32_e32 v145, v145, v119
	s_waitcnt vmcnt(36)
	v_log_f32_e32 v120, v88
	v_log_f32_e32 v121, v89
	v_log_f32_e32 v122, v90
	v_log_f32_e32 v123, v91
	v_sub_f32_e32 v88, 1.0, v88
	v_sub_f32_e32 v89, 1.0, v89
	v_sub_f32_e32 v90, 1.0, v90
	v_sub_f32_e32 v91, 1.0, v91
	v_mul_f32_e32 v120, s12, v120
	v_mul_f32_e32 v121, s12, v121
	v_mul_f32_e32 v122, s12, v122
	v_mul_f32_e32 v123, s12, v123
	v_add_f32_e32 v145, v145, v120
	v_add_f32_e32 v145, v145, v121
	v_add_f32_e32 v145, v145, v122
	v_add_f32_e32 v145, v145, v123
	s_waitcnt vmcnt(32)
	v_log_f32_e32 v124, v92
	v_log_f32_e32 v125, v93
	v_log_f32_e32 v126, v94
	v_log_f32_e32 v127, v95
	v_sub_f32_e32 v92, 1.0, v92
	v_sub_f32_e32 v93, 1.0, v93
	v_sub_f32_e32 v94, 1.0, v94
	v_sub_f32_e32 v95, 1.0, v95
	v_mul_f32_e32 v124, s12, v124
	v_mul_f32_e32 v125, s12, v125
	v_mul_f32_e32 v126, s12, v126
	v_mul_f32_e32 v127, s12, v127
	v_add_f32_e32 v145, v145, v124
	v_add_f32_e32 v145, v145, v125
	v_add_f32_e32 v145, v145, v126
	v_add_f32_e32 v145, v145, v127

.Lpre_g_go:
	s_lshl_b32 s21, s20, 6
	s_add_u32 s22, s21, 0x28500000
	s_add_u32 s24, s94, s22
	s_addc_u32 s25, s95, 0
	s_lshl_b32 s21, s20, 9
	s_lshl_b32 s4, s18, 7
	s_add_u32 s21, s21, s4
	s_add_u32 s22, s21, 0x1c380000
	s_add_u32 s26, s94, s22
	s_addc_u32 s27, s95, 0
	s_mov_b64 s[28:29], s[26:27]
	s_add_u32 s22, s21, 0x2e5c0000
	s_add_u32 s30, s94, s22
	s_addc_u32 s31, s95, 0
	s_add_u32 s22, s21, 0x1e3c0000
	s_add_u32 s34, s94, s22
	s_addc_u32 s35, s95, 0
	global_load_dwordx4 v[128:131], v146, s[24:25]
	global_load_ushort v96, v143, s[34:35]
	global_load_ushort v97, v143, s[34:35] offset:512
	global_load_ushort v98, v143, s[34:35] offset:1024
	global_load_ushort v99, v143, s[34:35] offset:1536
	global_load_ushort v100, v143, s[34:35] offset:2048
	global_load_ushort v101, v143, s[34:35] offset:2560
	global_load_ushort v102, v143, s[34:35] offset:3072
	global_load_ushort v103, v143, s[34:35] offset:3584
	s_add_u32 s34, s34, 0x1000
	s_addc_u32 s35, s35, 0
	global_load_ushort v104, v143, s[34:35]
	global_load_ushort v105, v143, s[34:35] offset:512
	global_load_ushort v106, v143, s[34:35] offset:1024
	global_load_ushort v107, v143, s[34:35] offset:1536
	global_load_ushort v108, v143, s[34:35] offset:2048
	global_load_ushort v109, v143, s[34:35] offset:2560
	global_load_ushort v110, v143, s[34:35] offset:3072
	global_load_ushort v111, v143, s[34:35] offset:3584
	global_load_ushort v0, v143, s[26:27]
	global_load_ushort v1, v143, s[26:27] offset:512
	global_load_ushort v2, v143, s[26:27] offset:1024
	global_load_ushort v3, v143, s[26:27] offset:1536
	global_load_ushort v4, v143, s[26:27] offset:2048
	global_load_ushort v5, v143, s[26:27] offset:2560
	global_load_ushort v6, v143, s[26:27] offset:3072
	global_load_ushort v7, v143, s[26:27] offset:3584
	s_add_u32 s26, s26, 0x1000
	s_addc_u32 s27, s27, 0
	global_load_ushort v8, v143, s[26:27]
	global_load_ushort v9, v143, s[26:27] offset:512
	global_load_ushort v10, v143, s[26:27] offset:1024
	global_load_ushort v11, v143, s[26:27] offset:1536
	global_load_ushort v12, v143, s[26:27] offset:2048
	global_load_ushort v13, v143, s[26:27] offset:2560
	global_load_ushort v14, v143, s[26:27] offset:3072
	global_load_ushort v15, v143, s[26:27] offset:3584
	v_mov_b32_e32 v145, 0
	s_waitcnt vmcnt(32)
	ds_write_b128 v147, v[128:131]
	s_waitcnt lgkmcnt(0)
	ds_read_b128 v[16:19], v81 offset:0
	ds_read_b128 v[20:23], v81 offset:16
	ds_read_b128 v[24:27], v81 offset:32
	ds_read_b128 v[28:31], v81 offset:48
	ds_read_b128 v[176:179], v81 offset:64
	ds_read_b128 v[180:183], v81 offset:80
	ds_read_b128 v[184:187], v81 offset:96
	ds_read_b128 v[188:191], v81 offset:112
	ds_read_b128 v[192:195], v81 offset:128
	ds_read_b128 v[196:199], v81 offset:144
	ds_read_b128 v[200:203], v81 offset:160
	ds_read_b128 v[206:209], v81 offset:176
	s_waitcnt lgkmcnt(8)
	v_mov_b32_e32 v32, v80
	v_fmac_f32_e32 v32, v16, v64
	v_fmac_f32_e32 v32, v17, v65
	v_fmac_f32_e32 v32, v18, v66
	v_fmac_f32_e32 v32, v19, v67
	v_fmac_f32_e32 v32, v20, v68
	v_fmac_f32_e32 v32, v21, v69
	v_fmac_f32_e32 v32, v22, v70
	v_fmac_f32_e32 v32, v23, v71
	v_fmac_f32_e32 v32, v24, v72
	v_fmac_f32_e32 v32, v25, v73
	v_fmac_f32_e32 v32, v26, v74
	v_fmac_f32_e32 v32, v27, v75
	v_fmac_f32_e32 v32, v28, v76
	v_fmac_f32_e32 v32, v29, v77
	v_fmac_f32_e32 v32, v30, v78
	v_fmac_f32_e32 v32, v31, v79
	ds_read_b128 v[16:19], v81 offset:192
	ds_read_b128 v[20:23], v81 offset:208
	ds_read_b128 v[24:27], v81 offset:224
	ds_read_b128 v[28:31], v81 offset:240
	v_min_f32_e32 v33, 0, v32
	v_mul_f32_e64 v34, |v32|, s11
	v_exp_f32_e32 v34, v34
	s_nop 0
	v_add_f32_e32 v34, 1.0, v34
	v_log_f32_e32 v34, v34
	s_nop 0
	v_mul_f32_e32 v34, s12, v34
	v_sub_f32_e32 v33, v33, v34
	v_mul_f32_e32 v112, s13, v33
	v_add_f32_e32 v145, v145, v112
	s_waitcnt lgkmcnt(8)
	v_mov_b32_e32 v32, v80
	v_fmac_f32_e32 v32, v176, v64
	v_fmac_f32_e32 v32, v177, v65
	v_fmac_f32_e32 v32, v178, v66
	v_fmac_f32_e32 v32, v179, v67
	v_fmac_f32_e32 v32, v180, v68
	v_fmac_f32_e32 v32, v181, v69
	v_fmac_f32_e32 v32, v182, v70
	v_fmac_f32_e32 v32, v183, v71
	v_fmac_f32_e32 v32, v184, v72
	v_fmac_f32_e32 v32, v185, v73
	v_fmac_f32_e32 v32, v186, v74
	v_fmac_f32_e32 v32, v187, v75
	v_fmac_f32_e32 v32, v188, v76
	v_fmac_f32_e32 v32, v189, v77
	v_fmac_f32_e32 v32, v190, v78
	v_fmac_f32_e32 v32, v191, v79
	ds_read_b128 v[176:179], v81 offset:256
	ds_read_b128 v[180:183], v81 offset:272
	ds_read_b128 v[184:187], v81 offset:288
	ds_read_b128 v[188:191], v81 offset:304
	v_min_f32_e32 v33, 0, v32
	v_mul_f32_e64 v34, |v32|, s11
	v_exp_f32_e32 v34, v34
	s_nop 0
	v_add_f32_e32 v34, 1.0, v34
	v_log_f32_e32 v34, v34
	s_nop 0
	v_mul_f32_e32 v34, s12, v34
	v_sub_f32_e32 v33, v33, v34
	v_mul_f32_e32 v113, s13, v33
	v_add_f32_e32 v145, v145, v113
	s_waitcnt lgkmcnt(8)
	v_mov_b32_e32 v32, v80
	v_fmac_f32_e32 v32, v192, v64
	v_fmac_f32_e32 v32, v193, v65
	v_fmac_f32_e32 v32, v194, v66
	v_fmac_f32_e32 v32, v195, v67
	v_fmac_f32_e32 v32, v196, v68
	v_fmac_f32_e32 v32, v197, v69
	v_fmac_f32_e32 v32, v198, v70
	v_fmac_f32_e32 v32, v199, v71
	v_fmac_f32_e32 v32, v200, v72
	v_fmac_f32_e32 v32, v201, v73
	v_fmac_f32_e32 v32, v202, v74
	v_fmac_f32_e32 v32, v203, v75
	v_fmac_f32_e32 v32, v206, v76
	v_fmac_f32_e32 v32, v207, v77
	v_fmac_f32_e32 v32, v208, v78
	v_fmac_f32_e32 v32, v209, v79
	ds_read_b128 v[192:195], v81 offset:320
	ds_read_b128 v[196:199], v81 offset:336
	ds_read_b128 v[200:203], v81 offset:352
	ds_read_b128 v[206:209], v81 offset:368
	v_min_f32_e32 v33, 0, v32
	v_mul_f32_e64 v34, |v32|, s11
	v_exp_f32_e32 v34, v34
	s_nop 0
	v_add_f32_e32 v34, 1.0, v34
	v_log_f32_e32 v34, v34
	s_nop 0
	v_mul_f32_e32 v34, s12, v34
	v_sub_f32_e32 v33, v33, v34
	v_mul_f32_e32 v114, s13, v33
	v_add_f32_e32 v145, v145, v114
	s_waitcnt lgkmcnt(8)
	v_mov_b32_e32 v32, v80
	v_fmac_f32_e32 v32, v16, v64
	v_fmac_f32_e32 v32, v17, v65
	v_fmac_f32_e32 v32, v18, v66
	v_fmac_f32_e32 v32, v19, v67
	v_fmac_f32_e32 v32, v20, v68
	v_fmac_f32_e32 v32, v21, v69
	v_fmac_f32_e32 v32, v22, v70
	v_fmac_f32_e32 v32, v23, v71
	v_fmac_f32_e32 v32, v24, v72
	v_fmac_f32_e32 v32, v25, v73
	v_fmac_f32_e32 v32, v26, v74
	v_fmac_f32_e32 v32, v27, v75
	v_fmac_f32_e32 v32, v28, v76
	v_fmac_f32_e32 v32, v29, v77
	v_fmac_f32_e32 v32, v30, v78
	v_fmac_f32_e32 v32, v31, v79
	ds_read_b128 v[16:19], v81 offset:384
	ds_read_b128 v[20:23], v81 offset:400
	ds_read_b128 v[24:27], v81 offset:416
	ds_read_b128 v[28:31], v81 offset:432
	v_min_f32_e32 v33, 0, v32
	v_mul_f32_e64 v34, |v32|, s11
	v_exp_f32_e32 v34, v34
	s_nop 0
	v_add_f32_e32 v34, 1.0, v34
	v_log_f32_e32 v34, v34
	s_nop 0
	v_mul_f32_e32 v34, s12, v34
	v_sub_f32_e32 v33, v33, v34
	v_mul_f32_e32 v115, s13, v33
	v_add_f32_e32 v145, v145, v115
	s_waitcnt lgkmcnt(8)
	v_mov_b32_e32 v32, v80
	v_fmac_f32_e32 v32, v176, v64
	v_fmac_f32_e32 v32, v177, v65
	v_fmac_f32_e32 v32, v178, v66
	v_fmac_f32_e32 v32, v179, v67
	v_fmac_f32_e32 v32, v180, v68
	v_fmac_f32_e32 v32, v181, v69
	v_fmac_f32_e32 v32, v182, v70
	v_fmac_f32_e32 v32, v183, v71
	v_fmac_f32_e32 v32, v184, v72
	v_fmac_f32_e32 v32, v185, v73
	v_fmac_f32_e32 v32, v186, v74
	v_fmac_f32_e32 v32, v187, v75
	v_fmac_f32_e32 v32, v188, v76
	v_fmac_f32_e32 v32, v189, v77
	v_fmac_f32_e32 v32, v190, v78
	v_fmac_f32_e32 v32, v191, v79
	ds_read_b128 v[176:179], v81 offset:448
	ds_read_b128 v[180:183], v81 offset:464
	ds_read_b128 v[184:187], v81 offset:480
	ds_read_b128 v[188:191], v81 offset:496
	v_min_f32_e32 v33, 0, v32
	v_mul_f32_e64 v34, |v32|, s11
	v_exp_f32_e32 v34, v34
	s_nop 0
	v_add_f32_e32 v34, 1.0, v34
	v_log_f32_e32 v34, v34
	s_nop 0
	v_mul_f32_e32 v34, s12, v34
	v_sub_f32_e32 v33, v33, v34
	v_mul_f32_e32 v116, s13, v33
	v_add_f32_e32 v145, v145, v116
	s_waitcnt lgkmcnt(8)
	v_mov_b32_e32 v32, v80
	v_fmac_f32_e32 v32, v192, v64
	v_fmac_f32_e32 v32, v193, v65
	v_fmac_f32_e32 v32, v194, v66
	v_fmac_f32_e32 v32, v195, v67
	v_fmac_f32_e32 v32, v196, v68
	v_fmac_f32_e32 v32, v197, v69
	v_fmac_f32_e32 v32, v198, v70
	v_fmac_f32_e32 v32, v199, v71
	v_fmac_f32_e32 v32, v200, v72
	v_fmac_f32_e32 v32, v201, v73
	v_fmac_f32_e32 v32, v202, v74
	v_fmac_f32_e32 v32, v203, v75
	v_fmac_f32_e32 v32, v206, v76
	v_fmac_f32_e32 v32, v207, v77
	v_fmac_f32_e32 v32, v208, v78
	v_fmac_f32_e32 v32, v209, v79
	ds_read_b128 v[192:195], v81 offset:512
	ds_read_b128 v[196:199], v81 offset:528
	ds_read_b128 v[200:203], v81 offset:544
	ds_read_b128 v[206:209], v81 offset:560
	v_min_f32_e32 v33, 0, v32
	v_mul_f32_e64 v34, |v32|, s11
	v_exp_f32_e32 v34, v34
	s_nop 0
	v_add_f32_e32 v34, 1.0, v34
	v_log_f32_e32 v34, v34
	s_nop 0
	v_mul_f32_e32 v34, s12, v34
	v_sub_f32_e32 v33, v33, v34
	v_mul_f32_e32 v117, s13, v33
	v_add_f32_e32 v145, v145, v117
	s_waitcnt lgkmcnt(8)
	v_mov_b32_e32 v32, v80
	v_fmac_f32_e32 v32, v16, v64
	v_fmac_f32_e32 v32, v17, v65
	v_fmac_f32_e32 v32, v18, v66
	v_fmac_f32_e32 v32, v19, v67
	v_fmac_f32_e32 v32, v20, v68
	v_fmac_f32_e32 v32, v21, v69
	v_fmac_f32_e32 v32, v22, v70
	v_fmac_f32_e32 v32, v23, v71
	v_fmac_f32_e32 v32, v24, v72
	v_fmac_f32_e32 v32, v25, v73
	v_fmac_f32_e32 v32, v26, v74
	v_fmac_f32_e32 v32, v27, v75
	v_fmac_f32_e32 v32, v28, v76
	v_fmac_f32_e32 v32, v29, v77
	v_fmac_f32_e32 v32, v30, v78
	v_fmac_f32_e32 v32, v31, v79
	ds_read_b128 v[16:19], v81 offset:576
	ds_read_b128 v[20:23], v81 offset:592
	ds_read_b128 v[24:27], v81 offset:608
	ds_read_b128 v[28:31], v81 offset:624
	v_min_f32_e32 v33, 0, v32
	v_mul_f32_e64 v34, |v32|, s11
	v_exp_f32_e32 v34, v34
	s_nop 0
	v_add_f32_e32 v34, 1.0, v34
	v_log_f32_e32 v34, v34
	s_nop 0
	v_mul_f32_e32 v34, s12, v34
	v_sub_f32_e32 v33, v33, v34
	v_mul_f32_e32 v118, s13, v33
	v_add_f32_e32 v145, v145, v118
	s_waitcnt lgkmcnt(8)
	v_mov_b32_e32 v32, v80
	v_fmac_f32_e32 v32, v176, v64
	v_fmac_f32_e32 v32, v177, v65
	v_fmac_f32_e32 v32, v178, v66
	v_fmac_f32_e32 v32, v179, v67
	v_fmac_f32_e32 v32, v180, v68
	v_fmac_f32_e32 v32, v181, v69
	v_fmac_f32_e32 v32, v182, v70
	v_fmac_f32_e32 v32, v183, v71
	v_fmac_f32_e32 v32, v184, v72
	v_fmac_f32_e32 v32, v185, v73
	v_fmac_f32_e32 v32, v186, v74
	v_fmac_f32_e32 v32, v187, v75
	v_fmac_f32_e32 v32, v188, v76
	v_fmac_f32_e32 v32, v189, v77
	v_fmac_f32_e32 v32, v190, v78
	v_fmac_f32_e32 v32, v191, v79
	ds_read_b128 v[176:179], v81 offset:640
	ds_read_b128 v[180:183], v81 offset:656
	ds_read_b128 v[184:187], v81 offset:672
	ds_read_b128 v[188:191], v81 offset:688
	v_min_f32_e32 v33, 0, v32
	v_mul_f32_e64 v34, |v32|, s11
	v_exp_f32_e32 v34, v34
	s_nop 0
	v_add_f32_e32 v34, 1.0, v34
	v_log_f32_e32 v34, v34
	s_nop 0
	v_mul_f32_e32 v34, s12, v34
	v_sub_f32_e32 v33, v33, v34
	v_mul_f32_e32 v119, s13, v33
	v_add_f32_e32 v145, v145, v119
	s_waitcnt lgkmcnt(8)
	v_mov_b32_e32 v32, v80
	v_fmac_f32_e32 v32, v192, v64
	v_fmac_f32_e32 v32, v193, v65
	v_fmac_f32_e32 v32, v194, v66
	v_fmac_f32_e32 v32, v195, v67
	v_fmac_f32_e32 v32, v196, v68
	v_fmac_f32_e32 v32, v197, v69
	v_fmac_f32_e32 v32, v198, v70
	v_fmac_f32_e32 v32, v199, v71
	v_fmac_f32_e32 v32, v200, v72
	v_fmac_f32_e32 v32, v201, v73
	v_fmac_f32_e32 v32, v202, v74
	v_fmac_f32_e32 v32, v203, v75
	v_fmac_f32_e32 v32, v206, v76
	v_fmac_f32_e32 v32, v207, v77
	v_fmac_f32_e32 v32, v208, v78
	v_fmac_f32_e32 v32, v209, v79
	ds_read_b128 v[192:195], v81 offset:704
	ds_read_b128 v[196:199], v81 offset:720
	ds_read_b128 v[200:203], v81 offset:736
	ds_read_b128 v[206:209], v81 offset:752
	v_min_f32_e32 v33, 0, v32
	v_mul_f32_e64 v34, |v32|, s11
	v_exp_f32_e32 v34, v34
	s_nop 0
	v_add_f32_e32 v34, 1.0, v34
	v_log_f32_e32 v34, v34
	s_nop 0
	v_mul_f32_e32 v34, s12, v34
	v_sub_f32_e32 v33, v33, v34
	v_mul_f32_e32 v120, s13, v33
	v_add_f32_e32 v145, v145, v120
	s_waitcnt lgkmcnt(8)
	v_mov_b32_e32 v32, v80
	v_fmac_f32_e32 v32, v16, v64
	v_fmac_f32_e32 v32, v17, v65
	v_fmac_f32_e32 v32, v18, v66
	v_fmac_f32_e32 v32, v19, v67
	v_fmac_f32_e32 v32, v20, v68
	v_fmac_f32_e32 v32, v21, v69
	v_fmac_f32_e32 v32, v22, v70
	v_fmac_f32_e32 v32, v23, v71
	v_fmac_f32_e32 v32, v24, v72
	v_fmac_f32_e32 v32, v25, v73
	v_fmac_f32_e32 v32, v26, v74
	v_fmac_f32_e32 v32, v27, v75
	v_fmac_f32_e32 v32, v28, v76
	v_fmac_f32_e32 v32, v29, v77
	v_fmac_f32_e32 v32, v30, v78
	v_fmac_f32_e32 v32, v31, v79
	ds_read_b128 v[16:19], v81 offset:768
	ds_read_b128 v[20:23], v81 offset:784
	ds_read_b128 v[24:27], v81 offset:800
	ds_read_b128 v[28:31], v81 offset:816
	v_min_f32_e32 v33, 0, v32
	v_mul_f32_e64 v34, |v32|, s11
	v_exp_f32_e32 v34, v34
	s_nop 0
	v_add_f32_e32 v34, 1.0, v34
	v_log_f32_e32 v34, v34
	s_nop 0
	v_mul_f32_e32 v34, s12, v34
	v_sub_f32_e32 v33, v33, v34
	v_mul_f32_e32 v121, s13, v33
	v_add_f32_e32 v145, v145, v121
	s_waitcnt lgkmcnt(8)
	v_mov_b32_e32 v32, v80
	v_fmac_f32_e32 v32, v176, v64
	v_fmac_f32_e32 v32, v177, v65
	v_fmac_f32_e32 v32, v178, v66
	v_fmac_f32_e32 v32, v179, v67
	v_fmac_f32_e32 v32, v180, v68
	v_fmac_f32_e32 v32, v181, v69
	v_fmac_f32_e32 v32, v182, v70
	v_fmac_f32_e32 v32, v183, v71
	v_fmac_f32_e32 v32, v184, v72
	v_fmac_f32_e32 v32, v185, v73
	v_fmac_f32_e32 v32, v186, v74
	v_fmac_f32_e32 v32, v187, v75
	v_fmac_f32_e32 v32, v188, v76
	v_fmac_f32_e32 v32, v189, v77
	v_fmac_f32_e32 v32, v190, v78
	v_fmac_f32_e32 v32, v191, v79
	ds_read_b128 v[176:179], v81 offset:832
	ds_read_b128 v[180:183], v81 offset:848
	ds_read_b128 v[184:187], v81 offset:864
	ds_read_b128 v[188:191], v81 offset:880
	v_min_f32_e32 v33, 0, v32
	v_mul_f32_e64 v34, |v32|, s11
	v_exp_f32_e32 v34, v34
	s_nop 0
	v_add_f32_e32 v34, 1.0, v34
	v_log_f32_e32 v34, v34
	s_nop 0
	v_mul_f32_e32 v34, s12, v34
	v_sub_f32_e32 v33, v33, v34
	v_mul_f32_e32 v122, s13, v33
	v_add_f32_e32 v145, v145, v122
	s_waitcnt lgkmcnt(8)
	v_mov_b32_e32 v32, v80
	v_fmac_f32_e32 v32, v192, v64
	v_fmac_f32_e32 v32, v193, v65
	v_fmac_f32_e32 v32, v194, v66
	v_fmac_f32_e32 v32, v195, v67
	v_fmac_f32_e32 v32, v196, v68
	v_fmac_f32_e32 v32, v197, v69
	v_fmac_f32_e32 v32, v198, v70
	v_fmac_f32_e32 v32, v199, v71
	v_fmac_f32_e32 v32, v200, v72
	v_fmac_f32_e32 v32, v201, v73
	v_fmac_f32_e32 v32, v202, v74
	v_fmac_f32_e32 v32, v203, v75
	v_fmac_f32_e32 v32, v206, v76
	v_fmac_f32_e32 v32, v207, v77
	v_fmac_f32_e32 v32, v208, v78
	v_fmac_f32_e32 v32, v209, v79
	ds_read_b128 v[192:195], v81 offset:896
	ds_read_b128 v[196:199], v81 offset:912
	ds_read_b128 v[200:203], v81 offset:928
	ds_read_b128 v[206:209], v81 offset:944
	v_min_f32_e32 v33, 0, v32
	v_mul_f32_e64 v34, |v32|, s11
	v_exp_f32_e32 v34, v34
	s_nop 0
	v_add_f32_e32 v34, 1.0, v34
	v_log_f32_e32 v34, v34
	s_nop 0
	v_mul_f32_e32 v34, s12, v34
	v_sub_f32_e32 v33, v33, v34
	v_mul_f32_e32 v123, s13, v33
	v_add_f32_e32 v145, v145, v123
	s_waitcnt lgkmcnt(8)
	v_mov_b32_e32 v32, v80
	v_fmac_f32_e32 v32, v16, v64
	v_fmac_f32_e32 v32, v17, v65
	v_fmac_f32_e32 v32, v18, v66
	v_fmac_f32_e32 v32, v19, v67
	v_fmac_f32_e32 v32, v20, v68
	v_fmac_f32_e32 v32, v21, v69
	v_fmac_f32_e32 v32, v22, v70
	v_fmac_f32_e32 v32, v23, v71
	v_fmac_f32_e32 v32, v24, v72
	v_fmac_f32_e32 v32, v25, v73
	v_fmac_f32_e32 v32, v26, v74
	v_fmac_f32_e32 v32, v27, v75
	v_fmac_f32_e32 v32, v28, v76
	v_fmac_f32_e32 v32, v29, v77
	v_fmac_f32_e32 v32, v30, v78
	v_fmac_f32_e32 v32, v31, v79
	ds_read_b128 v[16:19], v81 offset:960
	ds_read_b128 v[20:23], v81 offset:976
	ds_read_b128 v[24:27], v81 offset:992
	ds_read_b128 v[28:31], v81 offset:1008
	v_min_f32_e32 v33, 0, v32
	v_mul_f32_e64 v34, |v32|, s11
	v_exp_f32_e32 v34, v34
	s_nop 0
	v_add_f32_e32 v34, 1.0, v34
	v_log_f32_e32 v34, v34
	s_nop 0
	v_mul_f32_e32 v34, s12, v34
	v_sub_f32_e32 v33, v33, v34
	v_mul_f32_e32 v124, s13, v33
	v_add_f32_e32 v145, v145, v124
	s_waitcnt lgkmcnt(8)
	v_mov_b32_e32 v32, v80
	v_fmac_f32_e32 v32, v176, v64
	v_fmac_f32_e32 v32, v177, v65
	v_fmac_f32_e32 v32, v178, v66
	v_fmac_f32_e32 v32, v179, v67
	v_fmac_f32_e32 v32, v180, v68
	v_fmac_f32_e32 v32, v181, v69
	v_fmac_f32_e32 v32, v182, v70
	v_fmac_f32_e32 v32, v183, v71
	v_fmac_f32_e32 v32, v184, v72
	v_fmac_f32_e32 v32, v185, v73
	v_fmac_f32_e32 v32, v186, v74
	v_fmac_f32_e32 v32, v187, v75
	v_fmac_f32_e32 v32, v188, v76
	v_fmac_f32_e32 v32, v189, v77
	v_fmac_f32_e32 v32, v190, v78
	v_fmac_f32_e32 v32, v191, v79
	v_min_f32_e32 v33, 0, v32
	v_mul_f32_e64 v34, |v32|, s11
	v_exp_f32_e32 v34, v34
	s_nop 0
	v_add_f32_e32 v34, 1.0, v34
	v_log_f32_e32 v34, v34
	s_nop 0
	v_mul_f32_e32 v34, s12, v34
	v_sub_f32_e32 v33, v33, v34
	v_mul_f32_e32 v125, s13, v33
	v_add_f32_e32 v145, v145, v125
	s_waitcnt lgkmcnt(4)
	v_mov_b32_e32 v32, v80
	v_fmac_f32_e32 v32, v192, v64
	v_fmac_f32_e32 v32, v193, v65
	v_fmac_f32_e32 v32, v194, v66
	v_fmac_f32_e32 v32, v195, v67
	v_fmac_f32_e32 v32, v196, v68
	v_fmac_f32_e32 v32, v197, v69
	v_fmac_f32_e32 v32, v198, v70
	v_fmac_f32_e32 v32, v199, v71
	v_fmac_f32_e32 v32, v200, v72
	v_fmac_f32_e32 v32, v201, v73
	v_fmac_f32_e32 v32, v202, v74
	v_fmac_f32_e32 v32, v203, v75
	v_fmac_f32_e32 v32, v206, v76
	v_fmac_f32_e32 v32, v207, v77
	v_fmac_f32_e32 v32, v208, v78
	v_fmac_f32_e32 v32, v209, v79
	v_min_f32_e32 v33, 0, v32
	v_mul_f32_e64 v34, |v32|, s11
	v_exp_f32_e32 v34, v34
	s_nop 0
	v_add_f32_e32 v34, 1.0, v34
	v_log_f32_e32 v34, v34
	s_nop 0
	v_mul_f32_e32 v34, s12, v34
	v_sub_f32_e32 v33, v33, v34
	v_mul_f32_e32 v126, s13, v33
	v_add_f32_e32 v145, v145, v126
	s_waitcnt lgkmcnt(0)
	v_mov_b32_e32 v32, v80
	v_fmac_f32_e32 v32, v16, v64
	v_fmac_f32_e32 v32, v17, v65
	v_fmac_f32_e32 v32, v18, v66
	v_fmac_f32_e32 v32, v19, v67
	v_fmac_f32_e32 v32, v20, v68
	v_fmac_f32_e32 v32, v21, v69
	v_fmac_f32_e32 v32, v22, v70
	v_fmac_f32_e32 v32, v23, v71
	v_fmac_f32_e32 v32, v24, v72
	v_fmac_f32_e32 v32, v25, v73
	v_fmac_f32_e32 v32, v26, v74
	v_fmac_f32_e32 v32, v27, v75
	v_fmac_f32_e32 v32, v28, v76
	v_fmac_f32_e32 v32, v29, v77
	v_fmac_f32_e32 v32, v30, v78
	v_fmac_f32_e32 v32, v31, v79
	v_min_f32_e32 v33, 0, v32
	v_mul_f32_e64 v34, |v32|, s11
	v_exp_f32_e32 v34, v34
	s_nop 0
	v_add_f32_e32 v34, 1.0, v34
	v_log_f32_e32 v34, v34
	s_nop 0
	v_mul_f32_e32 v34, s12, v34
	v_sub_f32_e32 v33, v33, v34
	v_mul_f32_e32 v127, s13, v33
	v_add_f32_e32 v145, v145, v127
